# cand28 + P2 sample-row tail as a 4-deep rolling prefetch (group j+4's five loads issued while group j is processed)
# speedup vs baseline: 1.0159x; 1.0029x over previous
.LBB0_601:
	s_ashr_i32 s0, s25, 6
	s_add_i32 s2, s0, s81
	s_cmp_gt_i32 s2, 31
	s_cbranch_scc1 .LBB0_603
	s_ashr_i32 s3, s2, 31
	s_lshl_b64 s[0:1], s[2:3], 15
	v_and_b32_e32 v1, 63, v1
	s_waitcnt lgkmcnt(0)
	s_add_u32 s0, s14, s0
	s_waitcnt vmcnt(3)
	v_mov_b32_e32 v67, 0
	s_addc_u32 s1, s15, s1
	v_lshlrev_b32_e32 v66, 4, v1
	v_lshl_add_u64 v[68:69], s[0:1], 0, v[66:67]
	s_mov_b64 s[0:1], 0x69984000
	v_lshl_add_u64 v[2:3], v[68:69], 0, s[0:1]
	s_mov_b32 s1, 0x69986000
	v_add_co_u32_e32 v4, vcc, s1, v68
	s_mov_b32 s0, 0x69985000
	s_nop 0
	v_addc_co_u32_e32 v5, vcc, 0, v69, vcc
	v_add_co_u32_e32 v6, vcc, s0, v68
	global_load_dwordx4 v[58:61], v[2:3], off offset:1024
	global_load_dwordx4 v[50:53], v[2:3], off offset:2048
	v_addc_co_u32_e32 v7, vcc, 0, v69, vcc
	global_load_dwordx4 v[46:49], v[4:5], off offset:-4096
	global_load_dwordx4 v[42:45], v[6:7], off offset:1024
	global_load_dwordx4 v[38:41], v[6:7], off offset:2048
	global_load_dwordx4 v[34:37], v[6:7], off offset:3072
	v_add_co_u32_e32 v6, vcc, 0x69984000, v68
	global_load_dwordx4 v[30:33], v[4:5], off
	global_load_dwordx4 v[26:29], v[4:5], off offset:1024
	v_addc_co_u32_e32 v7, vcc, 0, v69, vcc
	global_load_dwordx4 v[62:65], v[6:7], off
	global_load_dwordx4 v[54:57], v[2:3], off offset:3072
	global_load_dwordx4 v[22:25], v[4:5], off offset:2048
	s_mov_b32 s0, 0x69987000
	global_load_dwordx4 v[18:21], v[4:5], off offset:3072
	v_add_co_u32_e32 v70, vcc, s0, v68
	s_mov_b32 s0, 0xf800000
	s_nop 0
	v_addc_co_u32_e32 v71, vcc, 0, v69, vcc
	global_load_dwordx4 v[14:17], v[70:71], off
	global_load_dwordx4 v[10:13], v[70:71], off offset:1024
	global_load_dwordx4 v[6:9], v[70:71], off offset:2048
	global_load_dwordx4 v[2:5], v[70:71], off offset:3072
	s_waitcnt vmcnt(15)
	v_mov_b32_e32 v70, v59
	v_mov_b32_e32 v71, v60
	v_mov_b32_e32 v72, v58
	v_mov_b32_e32 v73, v61
	s_waitcnt vmcnt(13)
	v_mov_b32_e32 v78, v47
	v_mov_b32_e32 v79, v48
	v_mov_b32_e32 v80, v46
	v_mov_b32_e32 v81, v49
	s_waitcnt vmcnt(12)
	v_add_f32_e32 v82, v42, v43
	v_add_f32_e32 v84, v44, v45
	s_waitcnt vmcnt(11)
	v_mov_b32_e32 v83, v40
	v_mov_b32_e32 v85, v41
	s_waitcnt vmcnt(10)
	v_mov_b32_e32 v86, v35
	v_mov_b32_e32 v87, v36
	v_mov_b32_e32 v88, v34
	v_mov_b32_e32 v89, v37
	s_waitcnt vmcnt(7)
	v_mov_b32_e32 v94, v63
	v_mov_b32_e32 v95, v64
	v_mov_b32_e32 v96, v62
	v_mov_b32_e32 v97, v65
	v_pk_add_f32 v[70:71], v[70:71], v[72:73]
	v_pk_add_f32 v[78:79], v[78:79], v[80:81]
	v_pk_add_f32 v[80:81], v[82:83], v[84:85]
	v_pk_add_f32 v[82:83], v[86:87], v[88:89]
	v_pk_add_f32 v[86:87], v[94:95], v[96:97]
	v_pk_add_f32 v[70:71], v[70:71], v[70:71] op_sel:[0,1] op_sel_hi:[1,0]
	v_add_f32_e32 v72, v86, v87
	v_add_f32_e32 v74, v50, v51
	v_add_f32_e32 v76, v52, v53
	s_waitcnt vmcnt(6)
	v_mov_b32_e32 v73, v54
	v_mov_b32_e32 v75, v56
	v_mov_b32_e32 v77, v57
	v_mov_b32_e32 v71, v55
	v_add_f32_e32 v72, 0, v72
	v_pk_add_f32 v[74:75], v[74:75], v[76:77]
	v_pk_add_f32 v[70:71], v[72:73], v[70:71]
	v_pk_add_f32 v[76:77], v[78:79], v[78:79] op_sel:[0,1] op_sel_hi:[1,0]
	v_pk_add_f32 v[70:71], v[70:71], v[74:75]
	v_mov_b32_e32 v77, v39
	v_pk_add_f32 v[70:71], v[70:71], v[70:71] op_sel:[0,1] op_sel_hi:[1,0]
	v_pk_add_f32 v[78:79], v[82:83], v[82:83] op_sel:[0,1] op_sel_hi:[1,0]
	v_mov_b32_e32 v71, v38
	v_pk_add_f32 v[70:71], v[70:71], v[76:77]
	v_add_f32_e32 v90, v30, v31
	v_pk_add_f32 v[70:71], v[70:71], v[80:81]
	v_add_f32_e32 v92, v32, v33
	v_pk_add_f32 v[70:71], v[70:71], v[70:71] op_sel:[0,1] op_sel_hi:[1,0]
	v_mov_b32_e32 v91, v28
	v_mov_b32_e32 v93, v29
	v_mov_b32_e32 v79, v27
	v_mov_b32_e32 v71, v26
	v_pk_add_f32 v[84:85], v[90:91], v[92:93]
	v_pk_add_f32 v[70:71], v[70:71], v[78:79]
	s_waitcnt vmcnt(5)
	v_mov_b32_e32 v72, v23
	v_mov_b32_e32 v73, v24
	v_mov_b32_e32 v74, v22
	v_mov_b32_e32 v75, v25
	v_pk_add_f32 v[70:71], v[70:71], v[84:85]
	v_pk_add_f32 v[72:73], v[72:73], v[74:75]
	v_pk_add_f32 v[70:71], v[70:71], v[70:71] op_sel:[0,1] op_sel_hi:[1,0]
	v_pk_add_f32 v[72:73], v[72:73], v[72:73] op_sel:[0,1] op_sel_hi:[1,0]
	s_waitcnt vmcnt(4)
	v_add_f32_e32 v74, v18, v19
	v_add_f32_e32 v76, v20, v21
	s_waitcnt vmcnt(3)
	v_mov_b32_e32 v71, v14
	v_mov_b32_e32 v73, v15
	v_mov_b32_e32 v75, v16
	v_mov_b32_e32 v77, v17
	v_pk_add_f32 v[70:71], v[70:71], v[72:73]
	v_pk_add_f32 v[72:73], v[74:75], v[76:77]
	s_waitcnt vmcnt(2)
	v_mov_b32_e32 v74, v10
	v_pk_add_f32 v[70:71], v[70:71], v[72:73]
	v_mov_b32_e32 v72, v11
	v_mov_b32_e32 v73, v12
	v_mov_b32_e32 v75, v13
	v_pk_add_f32 v[72:73], v[72:73], v[74:75]
	v_pk_add_f32 v[70:71], v[70:71], v[70:71] op_sel:[0,1] op_sel_hi:[1,0]
	v_pk_add_f32 v[72:73], v[72:73], v[72:73] op_sel:[0,1] op_sel_hi:[1,0]
	s_waitcnt vmcnt(1)
	v_add_f32_e32 v74, v6, v7
	v_add_f32_e32 v76, v8, v9
	s_waitcnt vmcnt(0)
	v_mov_b32_e32 v71, v2
	v_mov_b32_e32 v73, v3
	v_mov_b32_e32 v75, v4
	v_mov_b32_e32 v77, v5
	v_pk_add_f32 v[70:71], v[70:71], v[72:73]
	v_pk_add_f32 v[72:73], v[74:75], v[76:77]
	s_nop 0
	v_pk_add_f32 v[70:71], v[70:71], v[72:73]
	s_nop 0
	v_add_f32_e32 v70, v70, v71
	v_mbcnt_hi_u32_b32 v71, -1, v234
	v_and_b32_e32 v72, 64, v71
	v_add_u32_e32 v72, 64, v72
	v_xor_b32_e32 v73, 1, v71
	v_cmp_lt_i32_e32 vcc, v73, v72
	s_nop 1
	v_cndmask_b32_e32 v73, v71, v73, vcc
	v_lshlrev_b32_e32 v78, 2, v73
	s_waitcnt lgkmcnt(0)
	s_nop 1
	v_add_f32_dpp v70, v70, v70 quad_perm:[1,0,3,2] row_mask:0xf bank_mask:0xf
	v_xor_b32_e32 v73, 2, v71
	v_cmp_lt_i32_e32 vcc, v73, v72
	s_nop 1
	v_cndmask_b32_e32 v73, v71, v73, vcc
	v_lshlrev_b32_e32 v84, 2, v73
	s_waitcnt lgkmcnt(0)
	s_nop 1
	v_add_f32_dpp v70, v70, v70 quad_perm:[2,3,0,1] row_mask:0xf bank_mask:0xf
	v_xor_b32_e32 v73, 4, v71
	v_cmp_lt_i32_e32 vcc, v73, v72
	s_nop 1
	v_cndmask_b32_e32 v73, v71, v73, vcc
	v_lshlrev_b32_e32 v85, 2, v73
	s_waitcnt lgkmcnt(0)
	s_nop 1
	v_add_f32_dpp v70, v70, v70 row_half_mirror row_mask:0xf bank_mask:0xf
	v_xor_b32_e32 v73, 8, v71
	v_cmp_lt_i32_e32 vcc, v73, v72
	s_nop 1
	v_cndmask_b32_e32 v73, v71, v73, vcc
	v_lshlrev_b32_e32 v86, 2, v73
	s_waitcnt lgkmcnt(0)
	s_nop 1
	v_add_f32_dpp v70, v70, v70 row_mirror row_mask:0xf bank_mask:0xf
	v_xor_b32_e32 v73, 16, v71
	v_cmp_lt_i32_e32 vcc, v73, v72
	s_nop 1
	v_cndmask_b32_e32 v73, v71, v73, vcc
	v_lshlrev_b32_e32 v87, 2, v73
	s_waitcnt lgkmcnt(0)
	v_mov_b32_e32 v73, v70
	s_nop 1
	v_permlane16_swap_b32_e32 v73, v70
	v_add_f32_e32 v70, v70, v73
	v_xor_b32_e32 v73, 32, v71
	v_cmp_lt_i32_e32 vcc, v73, v72
	s_nop 1
	v_cndmask_b32_e32 v71, v71, v73, vcc
	v_lshlrev_b32_e32 v88, 2, v71
	s_waitcnt lgkmcnt(0)
	v_mov_b32_e32 v79, v70
	v_mov_b32_e32 v71, v70
	s_nop 1
	v_permlane32_swap_b32_e32 v71, v79
	v_add_f32_e32 v79, v79, v71
	v_fmamk_f32 v75, v79, 0xb9800000, v63
	v_fmamk_f32 v74, v79, 0xb9800000, v62
	v_fmamk_f32 v65, v79, 0xb9800000, v65
	v_fmac_f32_e32 v64, 0xb9800000, v79
	v_pk_mul_f32 v[62:63], v[64:65], v[64:65]
	v_pk_mul_f32 v[70:71], v[74:75], v[74:75]
	v_fmamk_f32 v61, v79, 0xb9800000, v61
	v_pk_mov_b32 v[72:73], v[70:71], v[62:63] op_sel:[1,0]
	v_mov_b32_e32 v71, v63
	v_pk_add_f32 v[62:63], v[72:73], v[70:71]
	v_fmamk_f32 v73, v79, 0xb9800000, v59
	v_fmamk_f32 v72, v79, 0xb9800000, v58
	v_fmac_f32_e32 v60, 0xb9800000, v79
	v_pk_mul_f32 v[58:59], v[60:61], v[60:61]
	v_pk_mul_f32 v[70:71], v[72:73], v[72:73]
	v_fmac_f32_e32 v54, 0xb9800000, v79
	v_pk_mov_b32 v[76:77], v[70:71], v[58:59] op_sel:[1,0]
	v_mov_b32_e32 v71, v59
	v_pk_add_f32 v[76:77], v[76:77], v[70:71]
	v_fmamk_f32 v71, v79, 0xb9800000, v51
	v_fmamk_f32 v70, v79, 0xb9800000, v50
	v_fmamk_f32 v58, v79, 0xb9800000, v56
	v_fmamk_f32 v55, v79, 0xb9800000, v55
	v_mul_f32_e32 v56, v54, v54
	v_pk_add_f32 v[50:51], v[62:63], v[62:63] op_sel:[0,1] op_sel_hi:[1,0]
	v_fmamk_f32 v59, v79, 0xb9800000, v57
	v_mul_f32_e32 v80, v55, v55
	v_mov_b32_e32 v51, v56
	v_pk_add_f32 v[56:57], v[76:77], v[76:77] op_sel:[0,1] op_sel_hi:[1,0]
	v_fmamk_f32 v53, v79, 0xb9800000, v53
	v_mov_b32_e32 v57, v80
	v_fmac_f32_e32 v52, 0xb9800000, v79
	v_pk_add_f32 v[50:51], v[50:51], v[56:57]
	v_mul_f32_e32 v56, v71, v71
	v_mul_f32_e32 v62, v53, v53
	v_mul_f32_e32 v81, v58, v58
	v_mul_f32_e32 v82, v59, v59
	v_pk_fma_f32 v[56:57], v[70:71], v[70:71], v[56:57] op_sel_hi:[1,1,0]
	v_pk_fma_f32 v[62:63], v[52:53], v[52:53], v[62:63] op_sel_hi:[1,1,0]
	v_mov_b32_e32 v57, v81
	v_mov_b32_e32 v63, v82
	v_pk_add_f32 v[56:57], v[56:57], v[62:63]
	v_fmamk_f32 v49, v79, 0xb9800000, v49
	v_pk_add_f32 v[62:63], v[50:51], v[56:57]
	v_fmamk_f32 v57, v79, 0xb9800000, v47
	v_fmamk_f32 v56, v79, 0xb9800000, v46
	v_fmac_f32_e32 v48, 0xb9800000, v79
	v_pk_mul_f32 v[46:47], v[48:49], v[48:49]
	v_pk_mul_f32 v[50:51], v[56:57], v[56:57]
	v_fmac_f32_e32 v38, 0xb9800000, v79
	v_pk_mov_b32 v[76:77], v[50:51], v[46:47] op_sel:[1,0]
	v_mov_b32_e32 v51, v47
	v_pk_add_f32 v[76:77], v[76:77], v[50:51]
	v_fmamk_f32 v50, v79, 0xb9800000, v42
	v_fmamk_f32 v47, v79, 0xb9800000, v41
	v_fmamk_f32 v46, v79, 0xb9800000, v40
	v_fmamk_f32 v39, v79, 0xb9800000, v39
	v_mul_f32_e32 v42, v38, v38
	v_pk_add_f32 v[40:41], v[62:63], v[62:63] op_sel:[0,1] op_sel_hi:[1,0]
	v_fmamk_f32 v51, v79, 0xb9800000, v43
	v_mul_f32_e32 v80, v39, v39
	v_mov_b32_e32 v41, v42
	v_pk_add_f32 v[42:43], v[76:77], v[76:77] op_sel:[0,1] op_sel_hi:[1,0]
	v_fmamk_f32 v45, v79, 0xb9800000, v45
	v_mov_b32_e32 v43, v80
	v_fmac_f32_e32 v44, 0xb9800000, v79
	v_pk_add_f32 v[40:41], v[40:41], v[42:43]
	v_mul_f32_e32 v42, v51, v51
	v_mul_f32_e32 v62, v45, v45
	v_mul_f32_e32 v81, v46, v46
	v_mul_f32_e32 v82, v47, v47
	v_pk_fma_f32 v[42:43], v[50:51], v[50:51], v[42:43] op_sel_hi:[1,1,0]
	v_pk_fma_f32 v[62:63], v[44:45], v[44:45], v[62:63] op_sel_hi:[1,1,0]
	v_mov_b32_e32 v43, v81
	v_mov_b32_e32 v63, v82
	v_pk_add_f32 v[42:43], v[42:43], v[62:63]
	v_fmamk_f32 v37, v79, 0xb9800000, v37
	v_pk_add_f32 v[62:63], v[40:41], v[42:43]
	v_fmamk_f32 v43, v79, 0xb9800000, v35
	v_fmamk_f32 v42, v79, 0xb9800000, v34
	v_fmac_f32_e32 v36, 0xb9800000, v79
	v_pk_mul_f32 v[34:35], v[36:37], v[36:37]
	v_pk_mul_f32 v[40:41], v[42:43], v[42:43]
	v_fmac_f32_e32 v26, 0xb9800000, v79
	v_pk_mov_b32 v[76:77], v[40:41], v[34:35] op_sel:[1,0]
	v_mov_b32_e32 v41, v35
	v_pk_add_f32 v[76:77], v[76:77], v[40:41]
	v_fmamk_f32 v40, v79, 0xb9800000, v30
	v_fmamk_f32 v35, v79, 0xb9800000, v29
	v_fmamk_f32 v34, v79, 0xb9800000, v28
	v_fmamk_f32 v27, v79, 0xb9800000, v27
	v_mul_f32_e32 v30, v26, v26
	v_pk_add_f32 v[28:29], v[62:63], v[62:63] op_sel:[0,1] op_sel_hi:[1,0]
	v_fmamk_f32 v41, v79, 0xb9800000, v31
	v_mul_f32_e32 v80, v27, v27
	v_mov_b32_e32 v29, v30
	v_pk_add_f32 v[30:31], v[76:77], v[76:77] op_sel:[0,1] op_sel_hi:[1,0]
	v_fmamk_f32 v33, v79, 0xb9800000, v33
	v_mov_b32_e32 v31, v80
	v_fmac_f32_e32 v32, 0xb9800000, v79
	v_pk_add_f32 v[28:29], v[28:29], v[30:31]
	v_mul_f32_e32 v30, v41, v41
	v_mul_f32_e32 v62, v33, v33
	v_mul_f32_e32 v81, v34, v34
	v_mul_f32_e32 v82, v35, v35
	v_pk_fma_f32 v[30:31], v[40:41], v[40:41], v[30:31] op_sel_hi:[1,1,0]
	v_pk_fma_f32 v[62:63], v[32:33], v[32:33], v[62:63] op_sel_hi:[1,1,0]
	v_mov_b32_e32 v31, v81
	v_mov_b32_e32 v63, v82
	v_pk_add_f32 v[30:31], v[30:31], v[62:63]
	v_fmamk_f32 v25, v79, 0xb9800000, v25
	v_pk_add_f32 v[28:29], v[28:29], v[30:31]
	v_fmamk_f32 v31, v79, 0xb9800000, v23
	v_fmamk_f32 v30, v79, 0xb9800000, v22
	v_fmac_f32_e32 v24, 0xb9800000, v79
	v_pk_mul_f32 v[22:23], v[24:25], v[24:25]
	v_pk_mul_f32 v[62:63], v[30:31], v[30:31]
	v_fmamk_f32 v15, v79, 0xb9800000, v15
	v_pk_mov_b32 v[76:77], v[62:63], v[22:23] op_sel:[1,0]
	v_mov_b32_e32 v63, v23
	v_pk_add_f32 v[62:63], v[76:77], v[62:63]
	v_fmac_f32_e32 v14, 0xb9800000, v79
	v_fmamk_f32 v23, v79, 0xb9800000, v19
	v_fmamk_f32 v22, v79, 0xb9800000, v18
	v_mul_f32_e32 v76, v14, v14
	v_mul_f32_e32 v77, v15, v15
	v_pk_add_f32 v[18:19], v[28:29], v[28:29] op_sel:[0,1] op_sel_hi:[1,0]
	v_pk_add_f32 v[28:29], v[62:63], v[62:63] op_sel:[0,1] op_sel_hi:[1,0]
	v_fmamk_f32 v21, v79, 0xb9800000, v21
	v_mov_b32_e32 v19, v76
	v_mov_b32_e32 v29, v77
	v_fmac_f32_e32 v20, 0xb9800000, v79
	v_fmamk_f32 v17, v79, 0xb9800000, v17
	v_fmamk_f32 v16, v79, 0xb9800000, v16
	v_pk_add_f32 v[18:19], v[18:19], v[28:29]
	v_mul_f32_e32 v28, v23, v23
	v_mul_f32_e32 v62, v21, v21
	v_mul_f32_e32 v80, v16, v16
	v_mul_f32_e32 v81, v17, v17
	v_pk_fma_f32 v[28:29], v[22:23], v[22:23], v[28:29] op_sel_hi:[1,1,0]
	v_pk_fma_f32 v[62:63], v[20:21], v[20:21], v[62:63] op_sel_hi:[1,1,0]
	v_mov_b32_e32 v29, v80
	v_mov_b32_e32 v63, v81
	v_pk_add_f32 v[28:29], v[28:29], v[62:63]
	v_fmamk_f32 v11, v79, 0xb9800000, v11
	v_fmamk_f32 v10, v79, 0xb9800000, v10
	v_fmamk_f32 v13, v79, 0xb9800000, v13
	v_fmac_f32_e32 v12, 0xb9800000, v79
	v_pk_add_f32 v[18:19], v[18:19], v[28:29]
	v_pk_mul_f32 v[28:29], v[12:13], v[12:13]
	v_pk_mul_f32 v[62:63], v[10:11], v[10:11]
	v_fmamk_f32 v3, v79, 0xb9800000, v3
	v_pk_mov_b32 v[76:77], v[62:63], v[28:29] op_sel:[1,0]
	v_mov_b32_e32 v63, v29
	v_pk_add_f32 v[28:29], v[76:77], v[62:63]
	v_fmac_f32_e32 v2, 0xb9800000, v79
	v_mul_f32_e32 v62, v2, v2
	v_mul_f32_e32 v63, v3, v3
	v_pk_add_f32 v[18:19], v[18:19], v[18:19] op_sel:[0,1] op_sel_hi:[1,0]
	v_pk_add_f32 v[28:29], v[28:29], v[28:29] op_sel:[0,1] op_sel_hi:[1,0]
	v_fmamk_f32 v7, v79, 0xb9800000, v7
	v_fmamk_f32 v9, v79, 0xb9800000, v9
	v_mov_b32_e32 v19, v62
	v_mov_b32_e32 v29, v63
	v_fmamk_f32 v6, v79, 0xb9800000, v6
	v_fmac_f32_e32 v8, 0xb9800000, v79
	v_fmamk_f32 v5, v79, 0xb9800000, v5
	v_fmamk_f32 v4, v79, 0xb9800000, v4
	v_pk_add_f32 v[18:19], v[18:19], v[28:29]
	v_mul_f32_e32 v28, v7, v7
	v_mul_f32_e32 v62, v9, v9
	v_mul_f32_e32 v76, v4, v4
	v_mul_f32_e32 v77, v5, v5
	v_pk_fma_f32 v[28:29], v[6:7], v[6:7], v[28:29] op_sel_hi:[1,1,0]
	v_pk_fma_f32 v[62:63], v[8:9], v[8:9], v[62:63] op_sel_hi:[1,1,0]
	v_mov_b32_e32 v29, v76
	v_mov_b32_e32 v63, v77
	v_pk_add_f32 v[28:29], v[28:29], v[62:63]
	s_nop 0
	v_pk_add_f32 v[18:19], v[18:19], v[28:29]
	s_nop 0
	v_add_f32_e32 v18, v18, v19
	global_load_dwordx4 v[76:79], v66, s[4:5]
	global_load_dwordx4 v[80:83], v66, s[6:7]
	s_waitcnt lgkmcnt(0)
	s_nop 1
	v_add_f32_dpp v18, v18, v18 quad_perm:[1,0,3,2] row_mask:0xf bank_mask:0xf
	s_waitcnt lgkmcnt(0)
	s_nop 1
	v_add_f32_dpp v18, v18, v18 quad_perm:[2,3,0,1] row_mask:0xf bank_mask:0xf
	s_waitcnt lgkmcnt(0)
	s_nop 1
	v_add_f32_dpp v18, v18, v18 row_half_mirror row_mask:0xf bank_mask:0xf
	v_lshlrev_b32_e32 v86, 3, v1
	v_mov_b32_e32 v1, 0x10000
	s_waitcnt lgkmcnt(0)
	s_nop 1
	v_add_f32_dpp v18, v18, v18 row_mirror row_mask:0xf bank_mask:0xf
	v_mov_b32_e32 v87, v67
	s_waitcnt lgkmcnt(0)
	v_mov_b32_e32 v19, v18
	s_nop 1
	v_permlane16_swap_b32_e32 v19, v18
	v_add_f32_e32 v18, v18, v19
	s_waitcnt lgkmcnt(0)
	v_mov_b32_e32 v19, v18
	s_nop 1
	v_permlane32_swap_b32_e32 v19, v18
	v_add_f32_e32 v18, v18, v19
	v_mov_b32_e32 v19, 0x358637bd
	v_fmac_f32_e32 v19, 0x39800000, v18
	v_mul_f32_e32 v18, 0x4f800000, v19
	v_cmp_gt_f32_e32 vcc, s0, v19
	s_nop 1
	v_cndmask_b32_e32 v18, v19, v18, vcc
	v_sqrt_f32_e32 v19, v18
	s_nop 0
	v_add_u32_e32 v28, -1, v19
	v_fma_f32 v29, -v28, v19, v18
	v_cmp_ge_f32_e64 s[0:1], 0, v29
	v_add_u32_e32 v29, 1, v19
	s_nop 0
	v_cndmask_b32_e64 v28, v19, v28, s[0:1]
	v_fma_f32 v19, -v29, v19, v18
	v_cmp_lt_f32_e64 s[0:1], 0, v19
	s_nop 1
	v_cndmask_b32_e64 v19, v28, v29, s[0:1]
	v_mul_f32_e32 v28, 0x37800000, v19
	v_cndmask_b32_e32 v19, v19, v28, vcc
	v_mov_b32_e32 v28, 0x260
	v_cmp_class_f32_e32 vcc, v18, v28
	s_nop 1
	v_cndmask_b32_e32 v18, v19, v18, vcc
	v_div_scale_f32 v19, s[0:1], v18, v18, 1.0
	v_rcp_f32_e32 v28, v19
	s_lshl_b64 s[0:1], s[2:3], 14
	s_add_u32 s0, s12, s0
	s_addc_u32 s1, s13, s1
	v_fma_f32 v29, -v19, v28, 1.0
	v_fmac_f32_e32 v28, v29, v28
	v_div_scale_f32 v29, vcc, 1.0, v18, 1.0
	v_mul_f32_e32 v62, v29, v28
	v_fma_f32 v63, -v19, v62, v29
	v_fmac_f32_e32 v62, v63, v28
	v_fma_f32 v19, -v19, v62, v29
	v_div_fmas_f32 v19, v19, v28, v62
	v_div_fixup_f32 v18, v19, v18, 1.0
	v_lshl_add_u64 v[62:63], s[0:1], 0, v[66:67]
	v_pk_mul_f32 v[64:65], v[18:19], v[64:65] op_sel_hi:[0,1]
	s_mov_b32 s0, 0x8881000
	v_pk_mul_f32 v[28:29], v[18:19], v[74:75] op_sel_hi:[0,1]
	s_waitcnt vmcnt(0)
	v_pk_fma_f32 v[78:79], v[78:79], v[64:65], v[82:83]
	v_add_co_u32_e32 v64, vcc, s0, v62
	v_pk_fma_f32 v[76:77], v[76:77], v[28:29], v[80:81]
	s_nop 0
	v_addc_co_u32_e32 v65, vcc, 0, v63, vcc
	s_mov_b32 s0, 0x69981000
	global_store_dwordx4 v[64:65], v[76:79], off offset:-4096
	v_add_co_u32_e32 v74, vcc, s0, v68
	global_load_dword v28, v67, s[8:9]
	global_load_dword v84, v67, s[10:11]
	v_addc_co_u32_e32 v75, vcc, 0, v69, vcc
	global_load_dwordx4 v[80:83], v[74:75], off offset:-4096
	v_mov_b64_e32 v[238:239], v[74:75]
	s_mov_b64 s[98:99], 0x2000
	v_lshl_add_u64 v[240:241], v[74:75], 0, s[98:99]
	v_add_u32_e32 v235, 0x400, v66
	global_load_dwordx4 v[192:195], v235, s[4:5]
	global_load_dwordx4 v[196:199], v235, s[6:7]
	v_mov_b32_e32 v236, 0x10000
	global_load_dword v204, v236, s[8:9]
	global_load_dword v205, v67, s[10:11] offset:512
	global_load_dwordx4 v[200:203], v[238:239], off offset:-3072
	v_add_u32_e32 v235, 0x800, v66
	global_load_dwordx4 v[206:209], v235, s[4:5]
	global_load_dwordx4 v[210:213], v235, s[6:7]
	v_mov_b32_e32 v236, 0x20000
	global_load_dword v218, v236, s[8:9]
	global_load_dword v219, v67, s[10:11] offset:1024
	global_load_dwordx4 v[214:217], v[238:239], off offset:-2048
	v_add_u32_e32 v235, 0xc00, v66
	global_load_dwordx4 v[220:223], v235, s[4:5]
	global_load_dwordx4 v[224:227], v235, s[6:7]
	v_mov_b32_e32 v236, 0x30000
	global_load_dword v232, v236, s[8:9]
	global_load_dword v233, v67, s[10:11] offset:1536
	global_load_dwordx4 v[228:231], v[238:239], off offset:-1024
	v_add_u32_e32 v235, 0x1000, v66
	global_load_dwordx4 v[178:181], v235, s[4:5]
	global_load_dwordx4 v[182:185], v235, s[6:7]
	v_mov_b32_e32 v236, 0x40000
	global_load_dword v190, v236, s[8:9]
	global_load_dword v191, v67, s[10:11] offset:2048
	global_load_dwordx4 v[186:189], v[238:239], off offset:0
	s_lshl_b64 s[0:1], s[2:3], 13
	s_add_u32 s0, s14, s0
	s_addc_u32 s1, s15, s1
	v_lshl_add_u64 v[86:87], s[0:1], 0, v[86:87]
	s_mov_b32 s0, 0x69a81000
	s_mov_b64 s[2:3], 0x8880000
	v_pk_mul_f32 v[60:61], v[18:19], v[60:61] op_sel_hi:[0,1]
	v_pk_mul_f32 v[72:73], v[18:19], v[72:73] op_sel_hi:[0,1]
	v_pk_mul_f32 v[52:53], v[18:19], v[52:53] op_sel_hi:[0,1]
	v_pk_mul_f32 v[70:71], v[18:19], v[70:71] op_sel_hi:[0,1]
	v_pk_mul_f32 v[58:59], v[18:19], v[58:59] op_sel_hi:[0,1]
	v_pk_mul_f32 v[48:49], v[18:19], v[48:49] op_sel_hi:[0,1]
	v_pk_mul_f32 v[56:57], v[18:19], v[56:57] op_sel_hi:[0,1]
	v_pk_mul_f32 v[44:45], v[18:19], v[44:45] op_sel_hi:[0,1]
	v_pk_mul_f32 v[46:47], v[18:19], v[46:47] op_sel_hi:[0,1]
	v_pk_mul_f32 v[38:39], v[18:19], v[38:39] op_sel_hi:[0,1]
	s_waitcnt vmcnt(21)
	v_pk_fma_f32 v[76:77], v[76:77], v[28:29], v[84:85] op_sel_hi:[1,0,0]
	v_pk_fma_f32 v[28:29], v[78:79], v[28:29], v[84:85] op_sel_hi:[1,0,0]
	v_lshl_add_u64 v[84:85], v[62:63], 0, s[2:3]
	s_waitcnt vmcnt(20)
	v_pk_mul_f32 v[28:29], v[82:83], v[28:29]
	v_pk_mul_f32 v[76:77], v[80:81], v[76:77]
	s_nop 0
	v_cvt_pk_bf16_f32 v76, v76, v77
	v_cvt_pk_bf16_f32 v77, v28, v29
	v_add_co_u32_e32 v28, vcc, s0, v86
	s_mov_b64 s[0:1], 0x69980000
	s_nop 0
	v_addc_co_u32_e32 v29, vcc, 0, v87, vcc
	global_store_dwordx2 v[28:29], v[76:77], off offset:-4096
	s_waitcnt vmcnt(16)
	v_mov_b64_e32 v[76:77], v[192:193]
	v_mov_b64_e32 v[78:79], v[194:195]
	s_nop 0
	v_mov_b64_e32 v[80:81], v[196:197]
	v_mov_b64_e32 v[82:83], v[198:199]
	v_lshl_add_u64 v[90:91], v[68:69], 0, s[0:1]
	s_mov_b64 s[0:1], 0x69a80000
	v_pk_fma_f32 v[76:77], v[76:77], v[72:73], v[80:81]
	v_pk_fma_f32 v[78:79], v[78:79], v[60:61], v[82:83]
	global_store_dwordx4 v[84:85], v[76:79], off offset:1024
	s_nop 1
	v_mov_b32_e32 v72, v204
	v_mov_b32_e32 v88, v205
	v_mov_b64_e32 v[80:81], v[200:201]
	v_mov_b64_e32 v[82:83], v[202:203]
	v_add_u32_e32 v235, 0x1400, v66
	global_load_dwordx4 v[192:195], v235, s[4:5]
	global_load_dwordx4 v[196:199], v235, s[6:7]
	v_mov_b32_e32 v236, 0x50000
	global_load_dword v204, v236, s[8:9]
	global_load_dword v205, v67, s[10:11] offset:2560
	global_load_dwordx4 v[200:203], v[238:239], off offset:1024
	v_lshl_add_u64 v[60:61], v[86:87], 0, s[0:1]
	v_mov_b32_e32 v1, 0x20000
	s_mov_b32 s0, 0x8883000
	s_mov_b32 s1, 0x69983000
	v_pk_fma_f32 v[76:77], v[76:77], v[72:73], v[88:89] op_sel_hi:[1,0,0]
	v_pk_fma_f32 v[72:73], v[78:79], v[72:73], v[88:89] op_sel_hi:[1,0,0]
	v_pk_mul_f32 v[76:77], v[80:81], v[76:77]
	v_pk_mul_f32 v[72:73], v[82:83], v[72:73]
	v_cvt_pk_bf16_f32 v76, v76, v77
	s_nop 0
	v_cvt_pk_bf16_f32 v77, v72, v73
	global_store_dwordx2 v[60:61], v[76:77], off offset:512
	s_waitcnt vmcnt(18)
	v_mov_b64_e32 v[76:77], v[206:207]
	v_mov_b64_e32 v[78:79], v[208:209]
	s_nop 0
	v_mov_b64_e32 v[80:81], v[210:211]
	v_mov_b64_e32 v[82:83], v[212:213]
	v_pk_fma_f32 v[70:71], v[76:77], v[70:71], v[80:81]
	v_pk_fma_f32 v[72:73], v[78:79], v[52:53], v[82:83]
	global_store_dwordx4 v[84:85], v[70:73], off offset:2048
	s_nop 1
	v_mov_b32_e32 v52, v218
	v_mov_b32_e32 v80, v219
	v_mov_b64_e32 v[76:77], v[214:215]
	v_mov_b64_e32 v[78:79], v[216:217]
	v_add_u32_e32 v235, 0x1800, v66
	global_load_dwordx4 v[206:209], v235, s[4:5]
	global_load_dwordx4 v[210:213], v235, s[6:7]
	v_mov_b32_e32 v236, 0x60000
	global_load_dword v218, v236, s[8:9]
	global_load_dword v219, v67, s[10:11] offset:3072
	global_load_dwordx4 v[214:217], v[238:239], off offset:2048
	v_mov_b32_e32 v1, 0x30000
	v_pk_fma_f32 v[70:71], v[70:71], v[52:53], v[80:81] op_sel_hi:[1,0,0]
	v_pk_fma_f32 v[52:53], v[72:73], v[52:53], v[80:81] op_sel_hi:[1,0,0]
	v_pk_mul_f32 v[70:71], v[76:77], v[70:71]
	v_pk_mul_f32 v[52:53], v[78:79], v[52:53]
	v_cvt_pk_bf16_f32 v70, v70, v71
	s_nop 0
	v_cvt_pk_bf16_f32 v71, v52, v53
	global_store_dwordx2 v[60:61], v[70:71], off offset:1024
	s_waitcnt vmcnt(20)
	v_mov_b64_e32 v[70:71], v[220:221]
	v_mov_b64_e32 v[72:73], v[222:223]
	s_nop 0
	v_mov_b64_e32 v[76:77], v[224:225]
	v_mov_b64_e32 v[78:79], v[226:227]
	v_pk_mul_f32 v[52:53], v[18:19], v[54:55] op_sel_hi:[0,1]
	v_pk_fma_f32 v[52:53], v[70:71], v[52:53], v[76:77]
	v_pk_fma_f32 v[54:55], v[72:73], v[58:59], v[78:79]
	global_store_dwordx4 v[84:85], v[52:55], off offset:3072
	s_nop 1
	v_mov_b32_e32 v58, v232
	v_mov_b32_e32 v76, v233
	v_mov_b64_e32 v[70:71], v[228:229]
	v_mov_b64_e32 v[72:73], v[230:231]
	v_add_u32_e32 v235, 0x1c00, v66
	global_load_dwordx4 v[220:223], v235, s[4:5]
	global_load_dwordx4 v[224:227], v235, s[6:7]
	v_mov_b32_e32 v236, 0x70000
	global_load_dword v232, v236, s[8:9]
	global_load_dword v233, v67, s[10:11] offset:3584
	global_load_dwordx4 v[228:231], v[238:239], off offset:3072
	v_or_b32_e32 v1, 0x1000, v66
	v_pk_fma_f32 v[52:53], v[52:53], v[58:59], v[76:77] op_sel_hi:[1,0,0]
	v_pk_fma_f32 v[54:55], v[54:55], v[58:59], v[76:77] op_sel_hi:[1,0,0]
	v_pk_mul_f32 v[52:53], v[70:71], v[52:53]
	v_pk_mul_f32 v[54:55], v[72:73], v[54:55]
	v_cvt_pk_bf16_f32 v52, v52, v53
	s_nop 0
	v_cvt_pk_bf16_f32 v53, v54, v55
	global_store_dwordx2 v[60:61], v[52:53], off offset:1536
	s_waitcnt vmcnt(22)
	v_mov_b64_e32 v[52:53], v[178:179]
	v_mov_b64_e32 v[54:55], v[180:181]
	s_nop 0
	v_mov_b64_e32 v[70:71], v[182:183]
	v_mov_b64_e32 v[72:73], v[184:185]
	v_mov_b32_e32 v1, 0x40000
	v_pk_fma_f32 v[52:53], v[52:53], v[56:57], v[70:71]
	v_pk_fma_f32 v[54:55], v[54:55], v[48:49], v[72:73]
	global_store_dwordx4 v[64:65], v[52:55], off
	s_nop 1
	v_mov_b32_e32 v48, v190
	v_mov_b32_e32 v70, v191
	v_mov_b64_e32 v[56:57], v[186:187]
	v_mov_b64_e32 v[58:59], v[188:189]
	v_add_u32_e32 v235, 0x2000, v66
	global_load_dwordx4 v[178:181], v235, s[4:5]
	global_load_dwordx4 v[182:185], v235, s[6:7]
	v_mov_b32_e32 v236, 0x80000
	global_load_dword v190, v236, s[8:9]
	v_mov_b32_e32 v237, 0x1000
	global_load_dword v191, v237, s[10:11]
	global_load_dwordx4 v[186:189], v[240:241], off offset:-4096
	v_or_b32_e32 v1, 0x1400, v66
	v_pk_fma_f32 v[52:53], v[52:53], v[48:49], v[70:71] op_sel_hi:[1,0,0]
	v_pk_fma_f32 v[48:49], v[54:55], v[48:49], v[70:71] op_sel_hi:[1,0,0]
	v_pk_mul_f32 v[52:53], v[56:57], v[52:53]
	v_pk_mul_f32 v[48:49], v[58:59], v[48:49]
	v_cvt_pk_bf16_f32 v52, v52, v53
	s_nop 0
	v_cvt_pk_bf16_f32 v53, v48, v49
	global_store_dwordx2 v[60:61], v[52:53], off offset:2048
	s_waitcnt vmcnt(22)
	v_mov_b64_e32 v[52:53], v[192:193]
	v_mov_b64_e32 v[54:55], v[194:195]
	s_nop 0
	v_mov_b64_e32 v[56:57], v[196:197]
	v_mov_b64_e32 v[58:59], v[198:199]
	v_pk_mul_f32 v[48:49], v[18:19], v[50:51] op_sel_hi:[0,1]
	v_mov_b32_e32 v1, 0x50000
	v_pk_fma_f32 v[48:49], v[52:53], v[48:49], v[56:57]
	v_pk_fma_f32 v[50:51], v[54:55], v[44:45], v[58:59]
	global_store_dwordx4 v[64:65], v[48:51], off offset:1024
	s_nop 1
	v_mov_b32_e32 v44, v204
	v_mov_b32_e32 v56, v205
	v_mov_b64_e32 v[52:53], v[200:201]
	v_mov_b64_e32 v[54:55], v[202:203]
	v_add_u32_e32 v235, 0x2400, v66
	global_load_dwordx4 v[192:195], v235, s[4:5]
	global_load_dwordx4 v[196:199], v235, s[6:7]
	v_mov_b32_e32 v236, 0x90000
	global_load_dword v204, v236, s[8:9]
	v_mov_b32_e32 v237, 0x1200
	global_load_dword v205, v237, s[10:11]
	global_load_dwordx4 v[200:203], v[240:241], off offset:-3072
	v_or_b32_e32 v1, 0x1800, v66
	v_pk_fma_f32 v[48:49], v[48:49], v[44:45], v[56:57] op_sel_hi:[1,0,0]
	v_pk_fma_f32 v[44:45], v[50:51], v[44:45], v[56:57] op_sel_hi:[1,0,0]
	v_pk_mul_f32 v[48:49], v[52:53], v[48:49]
	v_pk_mul_f32 v[44:45], v[54:55], v[44:45]
	v_cvt_pk_bf16_f32 v48, v48, v49
	s_nop 0
	v_cvt_pk_bf16_f32 v49, v44, v45
	global_store_dwordx2 v[60:61], v[48:49], off offset:2560
	s_waitcnt vmcnt(22)
	v_mov_b64_e32 v[48:49], v[206:207]
	v_mov_b64_e32 v[50:51], v[208:209]
	s_nop 0
	v_mov_b64_e32 v[52:53], v[210:211]
	v_mov_b64_e32 v[54:55], v[212:213]
	v_mov_b32_e32 v1, 0x60000
	v_pk_fma_f32 v[44:45], v[48:49], v[38:39], v[52:53]
	v_pk_fma_f32 v[46:47], v[50:51], v[46:47], v[54:55]
	global_store_dwordx4 v[64:65], v[44:47], off offset:2048
	s_nop 1
	v_mov_b32_e32 v38, v218
	v_mov_b32_e32 v52, v219
	v_mov_b64_e32 v[48:49], v[214:215]
	v_mov_b64_e32 v[50:51], v[216:217]
	v_add_u32_e32 v235, 0x2800, v66
	global_load_dwordx4 v[206:209], v235, s[4:5]
	global_load_dwordx4 v[210:213], v235, s[6:7]
	v_mov_b32_e32 v236, 0xa0000
	global_load_dword v218, v236, s[8:9]
	v_mov_b32_e32 v237, 0x1400
	global_load_dword v219, v237, s[10:11]
	global_load_dwordx4 v[214:217], v[240:241], off offset:-2048
	v_or_b32_e32 v1, 0x1c00, v66
	v_pk_fma_f32 v[44:45], v[44:45], v[38:39], v[52:53] op_sel_hi:[1,0,0]
	v_pk_fma_f32 v[38:39], v[46:47], v[38:39], v[52:53] op_sel_hi:[1,0,0]
	v_pk_mul_f32 v[44:45], v[48:49], v[44:45]
	v_pk_mul_f32 v[38:39], v[50:51], v[38:39]
	v_cvt_pk_bf16_f32 v44, v44, v45
	s_nop 0
	v_cvt_pk_bf16_f32 v45, v38, v39
	global_store_dwordx2 v[60:61], v[44:45], off offset:3072
	s_waitcnt vmcnt(22)
	v_mov_b64_e32 v[44:45], v[220:221]
	v_mov_b64_e32 v[46:47], v[222:223]
	s_nop 0
	v_mov_b64_e32 v[48:49], v[224:225]
	v_mov_b64_e32 v[50:51], v[226:227]
	v_pk_mul_f32 v[38:39], v[18:19], v[36:37] op_sel_hi:[0,1]
	v_pk_mul_f32 v[36:37], v[18:19], v[42:43] op_sel_hi:[0,1]
	v_mov_b32_e32 v1, 0x70000
	v_mov_b32_e32 v19, 0x1000
	v_pk_mul_f32 v[32:33], v[18:19], v[32:33] op_sel_hi:[0,1]
	v_pk_mul_f32 v[34:35], v[18:19], v[34:35] op_sel_hi:[0,1]
	v_pk_mul_f32 v[26:27], v[18:19], v[26:27] op_sel_hi:[0,1]
	v_pk_mul_f32 v[16:17], v[18:19], v[16:17] op_sel_hi:[0,1]
	v_pk_mul_f32 v[14:15], v[18:19], v[14:15] op_sel_hi:[0,1]
	v_pk_mul_f32 v[12:13], v[18:19], v[12:13] op_sel_hi:[0,1]
	v_pk_mul_f32 v[10:11], v[18:19], v[10:11] op_sel_hi:[0,1]
	v_pk_mul_f32 v[8:9], v[18:19], v[8:9] op_sel_hi:[0,1]
	v_pk_mul_f32 v[6:7], v[18:19], v[6:7] op_sel_hi:[0,1]
	v_pk_mul_f32 v[4:5], v[18:19], v[4:5] op_sel_hi:[0,1]
	v_pk_mul_f32 v[2:3], v[18:19], v[2:3] op_sel_hi:[0,1]
	v_pk_fma_f32 v[36:37], v[44:45], v[36:37], v[48:49]
	v_pk_fma_f32 v[38:39], v[46:47], v[38:39], v[50:51]
	global_store_dwordx4 v[64:65], v[36:39], off offset:3072
	s_nop 1
	v_mov_b32_e32 v46, v232
	v_mov_b32_e32 v48, v233
	v_mov_b64_e32 v[42:43], v[228:229]
	v_mov_b64_e32 v[44:45], v[230:231]
	v_add_u32_e32 v235, 0x2c00, v66
	global_load_dwordx4 v[220:223], v235, s[4:5]
	global_load_dwordx4 v[224:227], v235, s[6:7]
	v_mov_b32_e32 v236, 0xb0000
	global_load_dword v232, v236, s[8:9]
	v_mov_b32_e32 v237, 0x1600
	global_load_dword v233, v237, s[10:11]
	global_load_dwordx4 v[228:231], v[240:241], off offset:-1024
	v_or_b32_e32 v1, 0x2000, v66
	v_pk_fma_f32 v[36:37], v[36:37], v[46:47], v[48:49] op_sel_hi:[1,0,0]
	v_pk_fma_f32 v[38:39], v[38:39], v[46:47], v[48:49] op_sel_hi:[1,0,0]
	v_pk_mul_f32 v[36:37], v[42:43], v[36:37]
	v_pk_mul_f32 v[38:39], v[44:45], v[38:39]
	v_cvt_pk_bf16_f32 v36, v36, v37
	s_nop 0
	v_cvt_pk_bf16_f32 v37, v38, v39
	global_store_dwordx2 v[60:61], v[36:37], off offset:3584
	s_waitcnt vmcnt(22)
	v_mov_b64_e32 v[42:43], v[178:179]
	v_mov_b64_e32 v[44:45], v[180:181]
	v_mov_b64_e32 v[46:47], v[182:183]
	v_mov_b64_e32 v[48:49], v[184:185]
	v_add_co_u32_e32 v36, vcc, s0, v62
	v_pk_mul_f32 v[38:39], v[18:19], v[40:41] op_sel_hi:[0,1]
	s_nop 0
	v_addc_co_u32_e32 v37, vcc, 0, v63, vcc
	v_mov_b32_e32 v1, 0x80000
	s_mov_b32 s0, 0x8882000
	v_pk_fma_f32 v[38:39], v[42:43], v[38:39], v[46:47]
	v_pk_fma_f32 v[40:41], v[44:45], v[32:33], v[48:49]
	global_store_dwordx4 v[36:37], v[38:41], off offset:-4096
	v_add_co_u32_e32 v32, vcc, s1, v68
	s_nop 1
	v_mov_b32_e32 v46, v190
	v_mov_b32_e32 v48, v191
	v_addc_co_u32_e32 v33, vcc, 0, v69, vcc
	v_mov_b64_e32 v[42:43], v[186:187]
	v_mov_b64_e32 v[44:45], v[188:189]
	v_add_u32_e32 v235, 0x3000, v66
	global_load_dwordx4 v[178:181], v235, s[4:5]
	global_load_dwordx4 v[182:185], v235, s[6:7]
	v_mov_b32_e32 v236, 0xc0000
	global_load_dword v190, v236, s[8:9]
	v_mov_b32_e32 v237, 0x1800
	global_load_dword v191, v237, s[10:11]
	global_load_dwordx4 v[186:189], v[240:241], off offset:0
	v_or_b32_e32 v1, 0x2400, v66
	s_mov_b32 s1, 0x69982000
	v_pk_fma_f32 v[38:39], v[38:39], v[46:47], v[48:49] op_sel_hi:[1,0,0]
	v_pk_fma_f32 v[40:41], v[40:41], v[46:47], v[48:49] op_sel_hi:[1,0,0]
	v_add_co_u32_e32 v46, vcc, s0, v62
	v_pk_mul_f32 v[38:39], v[42:43], v[38:39]
	v_pk_mul_f32 v[40:41], v[44:45], v[40:41]
	v_cvt_pk_bf16_f32 v38, v38, v39
	v_addc_co_u32_e32 v47, vcc, 0, v63, vcc
	v_cvt_pk_bf16_f32 v39, v40, v41
	global_store_dwordx2 v[28:29], v[38:39], off
	s_waitcnt vmcnt(22)
	v_mov_b64_e32 v[38:39], v[192:193]
	v_mov_b64_e32 v[40:41], v[194:195]
	s_nop 0
	v_mov_b64_e32 v[42:43], v[196:197]
	v_mov_b64_e32 v[44:45], v[198:199]
	v_mov_b32_e32 v1, 0x90000
	v_add_co_u32_e32 v48, vcc, s1, v68
	v_pk_fma_f32 v[38:39], v[38:39], v[26:27], v[42:43]
	v_pk_fma_f32 v[40:41], v[40:41], v[34:35], v[44:45]
	global_store_dwordx4 v[46:47], v[38:41], off offset:1024
	s_nop 1
	v_mov_b32_e32 v26, v204
	v_mov_b32_e32 v34, v205
	v_addc_co_u32_e32 v49, vcc, 0, v69, vcc
	v_mov_b64_e32 v[42:43], v[200:201]
	v_mov_b64_e32 v[44:45], v[202:203]
	v_add_u32_e32 v235, 0x3400, v66
	global_load_dwordx4 v[192:195], v235, s[4:5]
	global_load_dwordx4 v[196:199], v235, s[6:7]
	v_mov_b32_e32 v236, 0xd0000
	global_load_dword v204, v236, s[8:9]
	v_mov_b32_e32 v237, 0x1a00
	global_load_dword v205, v237, s[10:11]
	global_load_dwordx4 v[200:203], v[240:241], off offset:1024
	v_or_b32_e32 v1, 0x2800, v66
	v_pk_fma_f32 v[38:39], v[38:39], v[26:27], v[34:35] op_sel_hi:[1,0,0]
	v_pk_fma_f32 v[26:27], v[40:41], v[26:27], v[34:35] op_sel_hi:[1,0,0]
	v_pk_mul_f32 v[34:35], v[42:43], v[38:39]
	v_pk_mul_f32 v[26:27], v[44:45], v[26:27]
	v_cvt_pk_bf16_f32 v34, v34, v35
	s_nop 0
	v_cvt_pk_bf16_f32 v35, v26, v27
	global_store_dwordx2 v[28:29], v[34:35], off offset:512
	s_waitcnt vmcnt(22)
	v_mov_b64_e32 v[38:39], v[206:207]
	v_mov_b64_e32 v[40:41], v[208:209]
	v_mov_b64_e32 v[42:43], v[210:211]
	v_mov_b64_e32 v[44:45], v[212:213]
	v_pk_mul_f32 v[26:27], v[18:19], v[24:25] op_sel_hi:[0,1]
	v_pk_mul_f32 v[24:25], v[18:19], v[30:31] op_sel_hi:[0,1]
	v_mov_b32_e32 v1, 0xa0000
	v_pk_fma_f32 v[24:25], v[38:39], v[24:25], v[42:43]
	v_pk_fma_f32 v[26:27], v[40:41], v[26:27], v[44:45]
	global_store_dwordx4 v[46:47], v[24:27], off offset:2048
	s_nop 1
	v_mov_b32_e32 v30, v218
	v_mov_b32_e32 v34, v219
	v_mov_b64_e32 v[38:39], v[214:215]
	v_mov_b64_e32 v[40:41], v[216:217]
	v_add_u32_e32 v235, 0x3800, v66
	global_load_dwordx4 v[206:209], v235, s[4:5]
	global_load_dwordx4 v[210:213], v235, s[6:7]
	v_mov_b32_e32 v236, 0xe0000
	global_load_dword v218, v236, s[8:9]
	v_mov_b32_e32 v237, 0x1c00
	global_load_dword v219, v237, s[10:11]
	global_load_dwordx4 v[214:217], v[240:241], off offset:2048
	v_or_b32_e32 v1, 0x2c00, v66
	v_pk_fma_f32 v[24:25], v[24:25], v[30:31], v[34:35] op_sel_hi:[1,0,0]
	v_pk_fma_f32 v[26:27], v[26:27], v[30:31], v[34:35] op_sel_hi:[1,0,0]
	v_pk_mul_f32 v[24:25], v[38:39], v[24:25]
	v_pk_mul_f32 v[26:27], v[40:41], v[26:27]
	v_cvt_pk_bf16_f32 v24, v24, v25
	v_pk_mul_f32 v[30:31], v[18:19], v[20:21] op_sel_hi:[0,1]
	v_cvt_pk_bf16_f32 v25, v26, v27
	global_store_dwordx2 v[28:29], v[24:25], off offset:1024
	s_waitcnt vmcnt(22)
	v_mov_b64_e32 v[24:25], v[220:221]
	v_mov_b64_e32 v[26:27], v[222:223]
	s_nop 0
	v_mov_b64_e32 v[38:39], v[224:225]
	v_mov_b64_e32 v[40:41], v[226:227]
	v_pk_mul_f32 v[20:21], v[18:19], v[22:23] op_sel_hi:[0,1]
	v_mov_b32_e32 v1, 0xb0000
	v_pk_fma_f32 v[20:21], v[24:25], v[20:21], v[38:39]
	v_pk_fma_f32 v[22:23], v[26:27], v[30:31], v[40:41]
	global_store_dwordx4 v[46:47], v[20:23], off offset:3072
	s_nop 1
	v_mov_b32_e32 v30, v232
	v_mov_b32_e32 v34, v233
	v_mov_b64_e32 v[24:25], v[228:229]
	v_mov_b64_e32 v[26:27], v[230:231]
	v_add_u32_e32 v235, 0x3c00, v66
	global_load_dwordx4 v[220:223], v235, s[4:5]
	global_load_dwordx4 v[224:227], v235, s[6:7]
	v_mov_b32_e32 v236, 0xf0000
	global_load_dword v232, v236, s[8:9]
	v_mov_b32_e32 v237, 0x1e00
	global_load_dword v233, v237, s[10:11]
	global_load_dwordx4 v[228:231], v[240:241], off offset:3072
	v_or_b32_e32 v1, 0x3000, v66
	v_pk_fma_f32 v[20:21], v[20:21], v[30:31], v[34:35] op_sel_hi:[1,0,0]
	v_pk_fma_f32 v[22:23], v[22:23], v[30:31], v[34:35] op_sel_hi:[1,0,0]
	v_pk_mul_f32 v[20:21], v[24:25], v[20:21]
	v_pk_mul_f32 v[22:23], v[26:27], v[22:23]
	v_cvt_pk_bf16_f32 v20, v20, v21
	s_nop 0
	v_cvt_pk_bf16_f32 v21, v22, v23
	global_store_dwordx2 v[28:29], v[20:21], off offset:1536
	s_waitcnt vmcnt(22)
	v_mov_b64_e32 v[20:21], v[178:179]
	v_mov_b64_e32 v[22:23], v[180:181]
	s_nop 0
	v_mov_b64_e32 v[24:25], v[182:183]
	v_mov_b64_e32 v[26:27], v[184:185]
	v_mov_b32_e32 v1, 0xc0000
	v_pk_fma_f32 v[14:15], v[20:21], v[14:15], v[24:25]
	v_pk_fma_f32 v[16:17], v[22:23], v[16:17], v[26:27]
	global_store_dwordx4 v[36:37], v[14:17], off
	s_nop 1
	v_mov_b32_e32 v24, v190
	v_mov_b32_e32 v26, v191
	v_mov_b64_e32 v[20:21], v[186:187]
	v_mov_b64_e32 v[22:23], v[188:189]
	v_or_b32_e32 v1, 0x3400, v66
	v_pk_fma_f32 v[14:15], v[14:15], v[24:25], v[26:27] op_sel_hi:[1,0,0]
	v_pk_fma_f32 v[16:17], v[16:17], v[24:25], v[26:27] op_sel_hi:[1,0,0]
	v_pk_mul_f32 v[14:15], v[20:21], v[14:15]
	v_pk_mul_f32 v[16:17], v[22:23], v[16:17]
	v_cvt_pk_bf16_f32 v14, v14, v15
	s_nop 0
	v_cvt_pk_bf16_f32 v15, v16, v17
	global_store_dwordx2 v[28:29], v[14:15], off offset:2048
	s_waitcnt vmcnt(17)
	v_mov_b64_e32 v[14:15], v[192:193]
	v_mov_b64_e32 v[16:17], v[194:195]
	s_nop 0
	v_mov_b64_e32 v[20:21], v[196:197]
	v_mov_b64_e32 v[22:23], v[198:199]
	v_mov_b32_e32 v1, 0xd0000
	v_pk_fma_f32 v[10:11], v[14:15], v[10:11], v[20:21]
	v_pk_fma_f32 v[12:13], v[16:17], v[12:13], v[22:23]
	global_store_dwordx4 v[36:37], v[10:13], off offset:1024
	s_nop 1
	v_mov_b32_e32 v20, v204
	v_mov_b32_e32 v22, v205
	v_mov_b64_e32 v[14:15], v[200:201]
	v_mov_b64_e32 v[16:17], v[202:203]
	v_or_b32_e32 v1, 0x3800, v66
	v_pk_fma_f32 v[10:11], v[10:11], v[20:21], v[22:23] op_sel_hi:[1,0,0]
	v_pk_fma_f32 v[12:13], v[12:13], v[20:21], v[22:23] op_sel_hi:[1,0,0]
	v_pk_mul_f32 v[10:11], v[14:15], v[10:11]
	v_pk_mul_f32 v[12:13], v[16:17], v[12:13]
	v_cvt_pk_bf16_f32 v10, v10, v11
	s_nop 0
	v_cvt_pk_bf16_f32 v11, v12, v13
	global_store_dwordx2 v[28:29], v[10:11], off offset:2560
	s_waitcnt vmcnt(12)
	v_mov_b64_e32 v[10:11], v[206:207]
	v_mov_b64_e32 v[12:13], v[208:209]
	s_nop 0
	v_mov_b64_e32 v[14:15], v[210:211]
	v_mov_b64_e32 v[16:17], v[212:213]
	v_mov_b32_e32 v1, 0xe0000
	v_pk_fma_f32 v[6:7], v[10:11], v[6:7], v[14:15]
	v_pk_fma_f32 v[8:9], v[12:13], v[8:9], v[16:17]
	global_store_dwordx4 v[36:37], v[6:9], off offset:2048
	s_nop 1
	v_mov_b32_e32 v14, v218
	v_mov_b32_e32 v16, v219
	v_mov_b64_e32 v[10:11], v[214:215]
	v_mov_b64_e32 v[12:13], v[216:217]
	v_or_b32_e32 v1, 0x3c00, v66
	v_pk_fma_f32 v[6:7], v[6:7], v[14:15], v[16:17] op_sel_hi:[1,0,0]
	v_pk_fma_f32 v[8:9], v[8:9], v[14:15], v[16:17] op_sel_hi:[1,0,0]
	v_pk_mul_f32 v[6:7], v[10:11], v[6:7]
	v_pk_mul_f32 v[8:9], v[12:13], v[8:9]
	v_cvt_pk_bf16_f32 v6, v6, v7
	s_nop 0
	v_cvt_pk_bf16_f32 v7, v8, v9
	global_store_dwordx2 v[28:29], v[6:7], off offset:3072
	s_waitcnt vmcnt(7)
	v_mov_b64_e32 v[6:7], v[220:221]
	v_mov_b64_e32 v[8:9], v[222:223]
	s_nop 0
	v_mov_b64_e32 v[10:11], v[224:225]
	v_mov_b64_e32 v[12:13], v[226:227]
	v_mov_b32_e32 v1, 0xf0000
	v_pk_fma_f32 v[2:3], v[6:7], v[2:3], v[10:11]
	v_pk_fma_f32 v[4:5], v[8:9], v[4:5], v[12:13]
	global_store_dwordx4 v[36:37], v[2:5], off offset:3072
	s_nop 1
	v_mov_b32_e32 v10, v232
	v_mov_b32_e32 v12, v233
	v_mov_b64_e32 v[6:7], v[228:229]
	v_mov_b64_e32 v[8:9], v[230:231]
	v_pk_fma_f32 v[2:3], v[2:3], v[10:11], v[12:13] op_sel_hi:[1,0,0]
	v_pk_fma_f32 v[4:5], v[4:5], v[10:11], v[12:13] op_sel_hi:[1,0,0]
	v_pk_mul_f32 v[2:3], v[6:7], v[2:3]
	v_pk_mul_f32 v[4:5], v[8:9], v[4:5]
	v_cvt_pk_bf16_f32 v2, v2, v3
	s_nop 0
	v_cvt_pk_bf16_f32 v3, v4, v5
	global_store_dwordx2 v[28:29], v[2:3], off offset:3584
